# residual GEMMs: panel-completion count deferred by one tile (no vector-memory drain between tiles; owner XCC id via scalar load), on top of v32
# baseline (speedup 1.0000x reference)
; __device__ __forceinline__ unsigned my_xcc_id() { return (unsigned)__builtin_amdgcn_s_getreg((3 << 11) | 20) & 0xFu; }
; __global__ void __launch_bounds__(512, 2) mega_fwd(Params p_arg) {
;     ...
;             if (nb == 256) {
;                 CountedStatic S; S.init(g.M, g.N, nb, bid); S.cnt = (unsigned*)(p->ws + WS_CNT); S.xcc_of = (const unsigned char*)(p->ws + WS_XCC); S.myx = my_xcc_id();
;                 pg8::gemm_phase<EpiResid, CountedStatic, true, true>(lds, g, S, E);
.LBB0_611:
	s_and_b64 vcc, exec, s[10:11]
	s_cbranch_vccz .LBB0_774
	s_waitcnt vmcnt(0)
	v_writelane_b32 v255, 0, 62
	v_mov_b32_e32 v20, v194
	s_cmpk_lt_i32 s6, 0x400
	s_getreg_b32 s18, hwreg(HW_REG_XCC_ID, 0, 4)
	s_cselect_b64 s[10:11], -1, 0
	s_cmpk_gt_i32 s6, 0x3ff
	v_readfirstlane_b32 s7, v20
	s_cbranch_scc1 .LBB0_618
	s_ashr_i32 s12, s6, 31
	s_lshr_b32 s12, s12, 29
	s_add_i32 s14, s6, s12
	s_and_b32 s12, s14, -8
	s_sub_i32 s15, s6, s12
	s_cmp_gt_i32 s15, -1
	s_mov_b64 s[12:13], -1
	s_cbranch_scc0 .LBB0_615
	s_lshl_b32 s16, s15, 7
	s_mov_b64 s[12:13], 0

;     __device__ __forceinline__ void done(const pg8::Unit& u) const {
;         asm volatile("s_waitcnt vmcnt(0)" ::: "memory");
;         const int owner = (u.pm >> 5) + 8 * ((u.pm & 7) + 8 * ((u.pm >> 3) & 3));
;         if ((unsigned)xcc_of[owner] != myx) { __builtin_amdgcn_fence(__ATOMIC_RELEASE, "agent"); asm volatile("s_waitcnt vmcnt(0)" ::: "memory"); }
;         if ((threadIdx.x & 63) == 0) __hip_atomic_fetch_add(cnt + 16 * u.pm, 1u, __ATOMIC_RELAXED, __HIP_MEMORY_SCOPE_AGENT);
;     __device__ __forceinline__ void operator()(const f32x4 (&acc)[2][2][4][2], const Unit& u, int wr, int wc, int fr, int fq) const {
;     ...
; #pragma unroll
;             for (int m2 = 0; m2 < 2; ++m2) {
;                 const int m = 2 * mh + m2;
;                 const size_t off = (size_t)(row0 + ai * 128 + m * 16) * DM + col0;
; #pragma unroll
;                 for (int bj = 0; bj < 2; ++bj)
; #pragma unroll
;                     for (int n = 0; n < 2; ++n) {
;                         const f32x4 x = (xv[m2][bj][n] - ms[m2].x) * ms[m2].y * gv[bj][n] + bv[bj][n];
;                         *(f32x4*)(dst + off + bj * 128 + n * 16) = x * DN_ALPHA + acc[ai][bj][m][n] * scale;
;                     }
;             }
;             asm volatile("" ::: "memory");
.LBB0_662:
	v_lshlrev_b64 v[68:69], 12, v[60:61]
	v_lshl_add_u64 v[70:71], v[224:225], 0, v[68:69]
	global_load_dwordx4 v[60:63], v[70:71], off
	global_load_dwordx4 v[64:67], v[70:71], off offset:64
	s_waitcnt vmcnt(5)
	v_cndmask_b32_e64 v54, v57, v54, s[12:13]
	v_sub_f32_e32 v73, v49, v56
	v_sub_f32_e32 v72, v48, v56
	v_sub_f32_e32 v75, v47, v56
	v_sub_f32_e32 v74, v46, v56
	global_load_dwordx4 v[46:49], v[70:71], off offset:512
	s_waitcnt vmcnt(5)
	v_sub_f32_e32 v45, v45, v56
	v_sub_f32_e32 v44, v44, v56
	v_sub_f32_e32 v43, v43, v56
	v_sub_f32_e32 v42, v42, v56
	s_waitcnt vmcnt(4)
	v_sub_f32_e32 v41, v41, v56
	v_sub_f32_e32 v40, v40, v56
	v_sub_f32_e32 v39, v39, v56
	v_sub_f32_e32 v38, v38, v56
	s_waitcnt vmcnt(3)
	v_cndmask_b32_e64 v50, v53, v50, s[12:13]
	v_sub_f32_e32 v77, v37, v56
	v_sub_f32_e32 v76, v36, v56
	v_sub_f32_e32 v57, v35, v56
	v_sub_f32_e32 v56, v34, v56
	global_load_dwordx4 v[34:37], v[70:71], off offset:576
	v_pk_mul_f32 v[70:71], v[54:55], v[74:75] op_sel_hi:[0,1]
	v_pk_mul_f32 v[72:73], v[54:55], v[72:73] op_sel_hi:[0,1]
	v_pk_mul_f32 v[38:39], v[54:55], v[38:39] op_sel_hi:[0,1]
	v_pk_mul_f32 v[40:41], v[54:55], v[40:41] op_sel_hi:[0,1]
	v_pk_mul_f32 v[42:43], v[54:55], v[42:43] op_sel_hi:[0,1]
	v_pk_mul_f32 v[44:45], v[54:55], v[44:45] op_sel_hi:[0,1]
	v_pk_mul_f32 v[56:57], v[54:55], v[56:57] op_sel_hi:[0,1]
	v_pk_mul_f32 v[54:55], v[54:55], v[76:77] op_sel_hi:[0,1]
	v_pk_fma_f32 v[72:73], v[108:109], v[72:73], v[112:113]
	v_pk_fma_f32 v[70:71], v[106:107], v[70:71], v[110:111]
	v_pk_fma_f32 v[40:41], v[124:125], v[40:41], v[128:129]
	v_pk_fma_f32 v[38:39], v[122:123], v[38:39], v[126:127]
	v_mov_b32_e32 v211, v210
	v_lshl_add_u64 v[58:59], s[48:49], 0, v[58:59]
	v_pk_fma_f32 v[44:45], v[100:101], v[44:45], v[104:105]
	v_pk_fma_f32 v[42:43], v[98:99], v[42:43], v[102:103]
	v_pk_fma_f32 v[54:55], v[116:117], v[54:55], v[120:121]
	v_pk_fma_f32 v[56:57], v[114:115], v[56:57], v[118:119]
	v_pk_mul_f32 v[70:71], v[70:71], s[88:89] op_sel_hi:[1,0]
	v_pk_mul_f32 v[72:73], v[72:73], s[88:89] op_sel_hi:[1,0]
	v_pk_mul_f32 v[38:39], v[38:39], s[88:89] op_sel_hi:[1,0]
	v_pk_mul_f32 v[40:41], v[40:41], s[88:89] op_sel_hi:[1,0]
	v_lshl_add_u64 v[58:59], v[58:59], 0, v[220:221]
	v_pk_mul_f32 v[42:43], v[42:43], s[88:89] op_sel_hi:[1,0]
	v_pk_mul_f32 v[44:45], v[44:45], s[88:89] op_sel_hi:[1,0]
	v_pk_mul_f32 v[56:57], v[56:57], s[88:89] op_sel_hi:[1,0]
	v_pk_mul_f32 v[54:55], v[54:55], s[88:89] op_sel_hi:[1,0]
	v_pk_fma_f32 v[32:33], v[32:33], v[210:211], v[72:73]
	v_pk_fma_f32 v[30:31], v[30:31], v[214:215], v[70:71]
	v_pk_fma_f32 v[24:25], v[24:25], v[210:211], v[40:41]
	v_pk_fma_f32 v[22:23], v[22:23], v[214:215], v[38:39]
	v_pk_fma_f32 v[28:29], v[28:29], v[210:211], v[44:45]
	v_pk_fma_f32 v[26:27], v[26:27], v[214:215], v[42:43]
	v_pk_fma_f32 v[20:21], v[20:21], v[210:211], v[54:55]
	v_pk_fma_f32 v[18:19], v[18:19], v[214:215], v[56:57]
	global_store_dwordx4 v[58:59], v[30:33], off
	global_store_dwordx4 v[58:59], v[26:29], off offset:64
	global_store_dwordx4 v[58:59], v[22:25], off offset:512
	global_store_dwordx4 v[58:59], v[18:21], off offset:576
	v_lshl_add_u64 v[68:69], s[48:49], 0, v[68:69]
	v_lshl_add_u64 v[68:69], v[68:69], 0, v[220:221]
	s_lshl_b32 s13, s44, 3
	s_ashr_i32 s12, s44, 5
	s_and_b32 s13, s13, 0xf8
	s_add_i32 s13, s13, s12
	s_ashr_i32 s33, s13, 31
	s_add_u32 s12, s90, s13
	s_addc_u32 s13, s91, s33
	s_waitcnt vmcnt(7)
	v_sub_f32_e32 v19, v63, v52
	s_waitcnt vmcnt(6)
	v_sub_f32_e32 v23, v67, v52
	v_sub_f32_e32 v22, v66, v52
	v_sub_f32_e32 v25, v65, v52
	v_sub_f32_e32 v24, v64, v52
	v_pk_mul_f32 v[24:25], v[50:51], v[24:25] op_sel_hi:[0,1]
	v_pk_mul_f32 v[22:23], v[50:51], v[22:23] op_sel_hi:[0,1]
	v_pk_fma_f32 v[22:23], v[100:101], v[22:23], v[104:105]
	v_pk_fma_f32 v[24:25], v[98:99], v[24:25], v[102:103]
	v_pk_mul_f32 v[22:23], v[22:23], s[88:89] op_sel_hi:[1,0]
	v_pk_mul_f32 v[24:25], v[24:25], s[88:89] op_sel_hi:[1,0]
	v_pk_fma_f32 v[12:13], v[12:13], v[210:211], v[22:23]
	v_pk_fma_f32 v[10:11], v[10:11], v[214:215], v[24:25]
	global_store_dwordx4 v[68:69], v[10:13], off offset:64
	v_sub_f32_e32 v18, v62, v52
	v_sub_f32_e32 v21, v61, v52
	s_waitcnt vmcnt(6)
	v_sub_f32_e32 v11, v49, v52
	v_sub_f32_e32 v10, v48, v52
	v_sub_f32_e32 v13, v47, v52
	v_sub_f32_e32 v12, v46, v52
	v_pk_mul_f32 v[12:13], v[50:51], v[12:13] op_sel_hi:[0,1]
	v_pk_mul_f32 v[10:11], v[50:51], v[10:11] op_sel_hi:[0,1]
	v_pk_fma_f32 v[10:11], v[124:125], v[10:11], v[128:129]
	v_pk_fma_f32 v[12:13], v[122:123], v[12:13], v[126:127]
	v_pk_mul_f32 v[10:11], v[10:11], s[88:89] op_sel_hi:[1,0]
	v_pk_mul_f32 v[12:13], v[12:13], s[88:89] op_sel_hi:[1,0]
	v_pk_fma_f32 v[8:9], v[8:9], v[210:211], v[10:11]
	v_pk_fma_f32 v[6:7], v[6:7], v[214:215], v[12:13]
	v_sub_f32_e32 v20, v60, v52
	global_store_dwordx4 v[68:69], v[6:9], off offset:512
	v_pk_mul_f32 v[20:21], v[50:51], v[20:21] op_sel_hi:[0,1]
	v_pk_mul_f32 v[18:19], v[50:51], v[18:19] op_sel_hi:[0,1]
	s_waitcnt vmcnt(6)
	v_sub_f32_e32 v7, v37, v52
	v_sub_f32_e32 v6, v36, v52
	v_sub_f32_e32 v9, v35, v52
	v_sub_f32_e32 v8, v34, v52
	v_pk_mul_f32 v[8:9], v[50:51], v[8:9] op_sel_hi:[0,1]
	v_pk_mul_f32 v[6:7], v[50:51], v[6:7] op_sel_hi:[0,1]
	v_pk_fma_f32 v[18:19], v[108:109], v[18:19], v[112:113]
	v_pk_fma_f32 v[20:21], v[106:107], v[20:21], v[110:111]
	v_pk_fma_f32 v[6:7], v[116:117], v[6:7], v[120:121]
	v_pk_fma_f32 v[8:9], v[114:115], v[8:9], v[118:119]
	v_pk_mul_f32 v[20:21], v[20:21], s[88:89] op_sel_hi:[1,0]
	v_pk_mul_f32 v[18:19], v[18:19], s[88:89] op_sel_hi:[1,0]
	v_pk_mul_f32 v[8:9], v[8:9], s[88:89] op_sel_hi:[1,0]
	v_pk_mul_f32 v[6:7], v[6:7], s[88:89] op_sel_hi:[1,0]
	v_pk_fma_f32 v[16:17], v[16:17], v[210:211], v[18:19]
	v_pk_fma_f32 v[14:15], v[14:15], v[214:215], v[20:21]
	v_pk_fma_f32 v[4:5], v[4:5], v[210:211], v[6:7]
	v_pk_fma_f32 v[2:3], v[2:3], v[214:215], v[8:9]
	global_store_dwordx4 v[68:69], v[14:17], off
	global_store_dwordx4 v[68:69], v[2:5], off offset:576
	v_readlane_b32 s38, v255, 62
	v_readlane_b32 s39, v255, 59
	v_readlane_b32 s33, v255, 61
	s_and_b32 s40, s12, 3
	s_and_b32 s12, s12, -4
	s_load_dword s41, s[12:13], 0x0
	s_lshl_b32 s40, s40, 3
	s_waitcnt lgkmcnt(0)
	s_lshr_b32 s41, s41, s40
	s_and_b32 s41, s41, 0xff
	s_cmp_eq_u32 s41, s96
	s_cselect_b32 s41, 1, 0
	v_writelane_b32 v255, s44, 59
	v_writelane_b32 v255, s41, 61
	v_writelane_b32 v255, 1, 62
	s_cmp_eq_u32 s38, 0
	s_cbranch_scc1 .Lrs_sig_done
	s_cmp_eq_u32 s33, 1
	s_cbranch_scc1 .Lrs_sig_same
	buffer_wbl2 sc1
	s_waitcnt vmcnt(0)
; #define PG8_WAIT_V(n) asm volatile("s_waitcnt vmcnt(" #n ")" ::: "memory")
; #define PG8_BAR __builtin_amdgcn_s_barrier()
; template <class Epi, class Sched, bool ALIGN_EPI = false, bool SP2 = false>
; __device__ __forceinline__ void gemm_phase(PG8_LAS unsigned char* lds, const Gemm g, const Sched& S, const Epi& E) {
;     ...
;     PG8_WAIT_V(0);
;     if constexpr (!ALIGN_EPI) { if (wr == 0) PG8_BAR; }
;     PG8_BAR;
;     __device__ __forceinline__ void done(const pg8::Unit& u) const {
;         asm volatile("s_waitcnt vmcnt(0)" ::: "memory");
;         const int owner = (u.pm >> 5) + 8 * ((u.pm & 7) + 8 * ((u.pm >> 3) & 3));
;         if ((unsigned)xcc_of[owner] != myx) { __builtin_amdgcn_fence(__ATOMIC_RELEASE, "agent"); asm volatile("s_waitcnt vmcnt(0)" ::: "memory"); }
;         if ((threadIdx.x & 63) == 0) __hip_atomic_fetch_add(cnt + 16 * u.pm, 1u, __ATOMIC_RELAXED, __HIP_MEMORY_SCOPE_AGENT);
.Lrs_sig_same:
	s_lshl_b32 s40, s39, 6
	v_readlane_b32 s12, v255, 46
	v_readlane_b32 s13, v255, 54
	s_nop 1
	s_add_u32 s40, s12, s40
	s_addc_u32 s41, s13, 0
	s_mov_b64 s[12:13], exec
	s_mov_b64 exec, 1
	v_mov_b32_e32 v2, 1
	s_nop 1
	global_atomic_add v1, v2, s[40:41]
	s_mov_b64 exec, s[12:13]
.Lrs_sig_done:
	s_and_b64 vcc, exec, s[10:11]
	s_mov_b64 s[10:11], -1
	s_cbranch_vccnz .LBB0_623
	s_andn2_b64 vcc, exec, s[16:17]
	s_cbranch_vccnz .LBB0_622
	s_barrier
	s_branch .LBB0_622
.LBB0_670:
	s_waitcnt vmcnt(0)
	v_readlane_b32 s38, v255, 62
	v_readlane_b32 s39, v255, 59
	v_readlane_b32 s33, v255, 61
	s_nop 1
	s_cmp_eq_u32 s38, 0
	s_cbranch_scc1 .Lrs_fin_done
	s_cmp_eq_u32 s33, 1
	s_cbranch_scc1 .Lrs_fin_same
	buffer_wbl2 sc1
	s_waitcnt vmcnt(0)
.Lrs_fin_same:
	s_lshl_b32 s40, s39, 6
	v_readlane_b32 s12, v255, 46
	v_readlane_b32 s13, v255, 54
	s_nop 1
	s_add_u32 s40, s12, s40
	s_addc_u32 s41, s13, 0
	s_mov_b64 s[12:13], exec
	s_mov_b64 exec, 1
	v_mov_b32_e32 v2, 1
	s_nop 1
	global_atomic_add v1, v2, s[40:41]
	s_mov_b64 exec, s[12:13]
	v_writelane_b32 v255, 0, 62
.Lrs_fin_done:
	v_readlane_b32 s2, v255, 41
	v_readlane_b32 s3, v255, 42
	v_readlane_b32 s74, v255, 43
	v_readlane_b32 s75, v255, 44
	s_mov_b32 s56, 0x10000
	s_movk_i32 s34, 0x5ff
	s_movk_i32 s35, 0xdff
	v_readlane_b32 s72, v255, 49
	s_mov_b64 s[36:37], 0x10000
	v_readlane_b32 s3, v255, 55
	s_barrier
